# S5 jobs: contiguous state-group ranges per XCD (groups 0-23 on XCD 0, 24-47 on XCD 1) so the jobs of an XCD share the input rows' cache lines
# speedup vs baseline: 1.0076x; 1.0034x over previous
;   __shared__ int sjob;
;   if (mode & 1)
;   for (int jb = blockIdx.x; jb < 176; jb += gridDim.x) {
;     if (jb < 48) { if (EN & 16) s5_job(p, l, jb, smem); }
;     else { if (EN & 32) mlstm_job(p, l, jb - 48, smem); }
;   }
.LBB0_421:
	s_mov_b64 s[0:1], 0
	v_writelane_b32 v255, s0, 22
	s_andn2_b64 vcc, exec, s[4:5]
	s_nop 0
	v_writelane_b32 v255, s1, 23
	s_cbranch_vccnz .LBB0_605
	v_readlane_b32 s0, v255, 24
	s_cmp_gt_i32 s0, 0
	s_mov_b64 s[4:5], -1
	s_cbranch_scc0 .LBB0_603
	v_readlane_b32 s0, v252, 0
	s_cmpk_lg_i32 s83, 0x100
	s_cbranch_scc1 .Ljm_plain
	s_and_b32 s38, s0, 7
	s_lshr_b32 vcc_lo, s0, 3
	s_cmp_lt_u32 s38, 2
	s_cbranch_scc0 .Ljm_ml
	s_mul_i32 s38, s38, 24
	s_add_i32 s38, s38, vcc_lo
	s_cmp_lt_u32 vcc_lo, 24
	s_cselect_b32 s38, s38, 0x100
	s_branch .Ljm_done
